# gu_strips pass B: K-tiles 2,3 prefetched into the freed save registers while tiles 0,1 (register-resident) are processed; vmcnt ladder dropped; on top of v025 design
# speedup vs baseline: 1.0140x; 1.0034x over previous
; __device__ __forceinline__ void gu_load(f32x4 (&v)[16], float& gA, float& gB, const GUDesc& d, int lane) {
;     const int kr = lane >> 3, nq = lane & 7;
;     const float* __restrict__ src = d.W + (size_t)(d.k0 + 4 * kr) * d.N + d.n0 + 4 * nq;
;     gA = d.gain ? d.gain[d.k0 + lane] : 1.0f; gB = d.gain ? d.gain[d.k0 + 64 + lane] : 1.0f;
; #pragma unroll
;     for (int i = 0; i < 16; ++i) v[i] = *(const f32x4*)(src + (size_t)(32 * (i >> 2) + (i & 3)) * d.N);
; }
; __device__ __forceinline__ void gu_strip(Frame& F, int uidx, int par) {
;     ...
;     for (int kt = F.wave; kt < nkt; kt += 8) {
;         f32x4 v[16]; float gA, gB; d.k0 = 128 * kt; gu_load(v, gA, gB, d, lane);
; #pragma unroll
;         for (int jq = 0; jq < 4; ++jq) {
; #pragma unroll
;             for (int e2 = 0; e2 < 4; ++e2) {
;                 const float g = jq < 2 ? __shfl(gA, 32 * jq + 4 * kr + e2) : __shfl(gB, 32 * (jq - 2) + 4 * kr + e2);
; #pragma unroll
;                 for (int e = 0; e < 4; ++e) cm[e] = fmaxf(cm[e], fabsf(v[4 * jq + e2][e] * g));
;             }
;         }
;     }
.LBB0_1082:
	v_mad_u64_u32 v[14:15], s[46:47], s16, v6, 0
	v_lshl_add_u64 v[26:27], v[14:15], 2, v[4:5]
	v_lshl_add_u64 v[30:31], v[26:27], 0, s[0:1]
	v_lshl_add_u64 v[34:35], v[30:31], 0, s[0:1]
	global_load_dwordx4 v[14:17], v[26:27], off
	s_waitcnt vmcnt(2)
	ds_bpermute_b32 v23, v41, v12
	global_load_dwordx4 v[26:29], v[30:31], off
	ds_bpermute_b32 v112, v42, v12
	global_load_dwordx4 v[30:33], v[34:35], off
	v_lshl_add_u64 v[34:35], v[34:35], 0, s[0:1]
	global_load_dwordx4 v[60:63], v[34:35], off
	v_lshl_add_u64 v[34:35], v[34:35], 0, s[18:19]
	global_load_dwordx4 v[64:67], v[34:35], off
	v_lshl_add_u64 v[34:35], v[34:35], 0, s[0:1]
	global_load_dwordx4 v[68:71], v[34:35], off
	v_lshl_add_u64 v[34:35], v[34:35], 0, s[0:1]
	global_load_dwordx4 v[72:75], v[34:35], off
	v_lshl_add_u64 v[34:35], v[34:35], 0, s[0:1]
	global_load_dwordx4 v[76:79], v[34:35], off
	v_lshl_add_u64 v[34:35], v[34:35], 0, s[18:19]
	global_load_dwordx4 v[80:83], v[34:35], off
	v_lshl_add_u64 v[34:35], v[34:35], 0, s[0:1]
	global_load_dwordx4 v[84:87], v[34:35], off
	v_lshl_add_u64 v[34:35], v[34:35], 0, s[0:1]
	global_load_dwordx4 v[88:91], v[34:35], off
	v_lshl_add_u64 v[34:35], v[34:35], 0, s[0:1]
	global_load_dwordx4 v[92:95], v[34:35], off
	ds_bpermute_b32 v113, v43, v12
	ds_bpermute_b32 v114, v44, v12
	ds_bpermute_b32 v115, v45, v12
	ds_bpermute_b32 v116, v46, v12
	ds_bpermute_b32 v117, v47, v12
	ds_bpermute_b32 v118, v48, v12
	v_lshl_add_u64 v[12:13], v[34:35], 0, s[18:19]
	global_load_dwordx4 v[96:99], v[12:13], off
	v_lshl_add_u64 v[12:13], v[12:13], 0, s[0:1]
	global_load_dwordx4 v[100:103], v[12:13], off
	v_lshl_add_u64 v[12:13], v[12:13], 0, s[0:1]
	global_load_dwordx4 v[104:107], v[12:13], off
	v_lshl_add_u64 v[12:13], v[12:13], 0, s[0:1]
	global_load_dwordx4 v[108:111], v[12:13], off
	s_waitcnt vmcnt(16)
	ds_bpermute_b32 v119, v41, v8
	s_add_i32 s17, s17, 8
	v_add_u32_e32 v6, 0x400, v6
	s_cmp_gt_u32 s17, 23
	v_add_u32_e32 v18, 0x400, v18
	s_waitcnt vmcnt(15) lgkmcnt(8)
	v_mov_b32_e32 v247, v14
	v_mov_b32_e32 v248, v15
	v_mov_b32_e32 v249, v16
	v_mov_b32_e32 v250, v17
	v_mul_f32_e32 v12, v14, v23
	v_mul_f32_e32 v14, v16, v23
	s_waitcnt vmcnt(14) lgkmcnt(7)
	v_mov_b32_e32 v251, v26
	v_mul_f32_e32 v16, v26, v112
	v_max3_f32 v10, v10, |v12|, |v16|
	s_waitcnt vmcnt(13) lgkmcnt(6)
	v_mul_f32_e32 v12, v30, v113
	v_mul_f32_e32 v13, v15, v23
	s_waitcnt vmcnt(12) lgkmcnt(5)
	v_mul_f32_e32 v16, v60, v114
	v_max3_f32 v10, v10, |v12|, |v16|
	s_waitcnt vmcnt(11) lgkmcnt(4)
	v_mul_f32_e32 v12, v64, v115
	v_mul_f32_e32 v15, v17, v23
	s_waitcnt vmcnt(10) lgkmcnt(3)
	v_mul_f32_e32 v16, v68, v116
	v_max3_f32 v10, v10, |v12|, |v16|
	s_waitcnt vmcnt(9) lgkmcnt(2)
	v_mul_f32_e32 v12, v72, v117
	v_mul_f32_e32 v17, v27, v112
	s_waitcnt vmcnt(8) lgkmcnt(1)
	v_mul_f32_e32 v16, v76, v118
	v_max3_f32 v10, v10, |v12|, |v16|
	ds_bpermute_b32 v12, v42, v8
	v_mul_f32_e32 v23, v28, v112
	v_max3_f32 v11, v11, |v13|, |v17|
	v_mul_f32_e32 v13, v31, v113
	v_mul_f32_e32 v17, v61, v114
	v_mul_f32_e32 v26, v29, v112
	v_max3_f32 v9, v9, |v14|, |v23|
	v_mul_f32_e32 v14, v32, v113
	v_mul_f32_e32 v23, v62, v114
	v_max3_f32 v11, v11, |v13|, |v17|
	v_mul_f32_e32 v13, v65, v115
	v_mul_f32_e32 v17, v69, v116
	v_max3_f32 v7, v7, |v15|, |v26|
	v_mul_f32_e32 v15, v33, v113
	v_mul_f32_e32 v26, v63, v114
	v_max3_f32 v9, v9, |v14|, |v23|
	v_mul_f32_e32 v14, v66, v115
	v_mul_f32_e32 v23, v70, v116
	v_max3_f32 v11, v11, |v13|, |v17|
	v_mul_f32_e32 v13, v73, v117
	v_mul_f32_e32 v17, v77, v118
	v_max3_f32 v7, v7, |v15|, |v26|
	v_mul_f32_e32 v15, v67, v115
	v_mul_f32_e32 v26, v71, v116
	v_max3_f32 v9, v9, |v14|, |v23|
	v_mul_f32_e32 v14, v74, v117
	v_mul_f32_e32 v23, v78, v118
	v_max3_f32 v11, v11, |v13|, |v17|
	s_waitcnt vmcnt(7) lgkmcnt(1)
	v_mul_f32_e32 v13, v80, v119
	s_waitcnt vmcnt(6) lgkmcnt(0)
	v_mul_f32_e32 v17, v84, v12
	v_max3_f32 v7, v7, |v15|, |v26|
	v_mul_f32_e32 v15, v75, v117
	v_mul_f32_e32 v26, v79, v118
	v_max3_f32 v9, v9, |v14|, |v23|
	v_mul_f32_e32 v14, v81, v119
	v_max3_f32 v10, v10, |v13|, |v17|
	v_mul_f32_e32 v13, v85, v12
	v_max3_f32 v7, v7, |v15|, |v26|
	v_mul_f32_e32 v16, v83, v119
	v_max3_f32 v11, v11, |v14|, |v13|
	v_mul_f32_e32 v13, v86, v12
	v_mul_f32_e32 v12, v87, v12
	ds_bpermute_b32 v14, v43, v8
	v_max3_f32 v7, v7, |v16|, |v12|
	ds_bpermute_b32 v12, v44, v8
	v_mul_f32_e32 v15, v82, v119
	v_max3_f32 v9, v9, |v15|, |v13|
	s_waitcnt vmcnt(5) lgkmcnt(1)
	v_mul_f32_e32 v13, v88, v14
	v_mul_f32_e32 v15, v89, v14
	s_waitcnt vmcnt(4) lgkmcnt(0)
	v_mul_f32_e32 v17, v92, v12
	v_max3_f32 v10, v10, |v13|, |v17|
	v_mul_f32_e32 v13, v93, v12
	v_mul_f32_e32 v16, v90, v14
	v_mul_f32_e32 v14, v91, v14
	v_max3_f32 v11, v11, |v15|, |v13|
	v_mul_f32_e32 v13, v94, v12
	v_mul_f32_e32 v12, v95, v12
	ds_bpermute_b32 v15, v45, v8
	v_max3_f32 v7, v7, |v14|, |v12|
	ds_bpermute_b32 v12, v46, v8
	v_max3_f32 v9, v9, |v16|, |v13|
	s_waitcnt vmcnt(3) lgkmcnt(1)
	v_mul_f32_e32 v13, v96, v15
	v_mul_f32_e32 v14, v97, v15
	s_waitcnt vmcnt(2) lgkmcnt(0)
	v_mul_f32_e32 v17, v100, v12
	v_max3_f32 v10, v10, |v13|, |v17|
	v_mul_f32_e32 v13, v101, v12
	v_max3_f32 v11, v11, |v14|, |v13|
	ds_bpermute_b32 v14, v47, v8
	ds_bpermute_b32 v8, v48, v8
	v_mul_f32_e32 v16, v98, v15
	v_mul_f32_e32 v15, v99, v15
	v_mul_f32_e32 v13, v102, v12
	v_mul_f32_e32 v12, v103, v12
	v_max3_f32 v9, v9, |v16|, |v13|
	v_max3_f32 v7, v7, |v15|, |v12|
	s_waitcnt vmcnt(1) lgkmcnt(1)
	v_mul_f32_e32 v12, v104, v14
	s_waitcnt vmcnt(0) lgkmcnt(0)
	v_mul_f32_e32 v16, v108, v8
	v_mul_f32_e32 v13, v105, v14
	v_max3_f32 v10, v10, |v12|, |v16|
	v_mul_f32_e32 v12, v109, v8
	v_mul_f32_e32 v15, v106, v14
	v_mul_f32_e32 v14, v107, v14
	v_max3_f32 v11, v11, |v13|, |v12|
	v_mul_f32_e32 v12, v110, v8
	v_mul_f32_e32 v8, v111, v8
	v_max3_f32 v9, v9, |v15|, |v12|
	v_max3_f32 v7, v7, |v14|, |v8|
	s_lshr_b32 s98, s17, 3
	s_cmp_eq_u32 s98, 0
	s_cbranch_scc1 .Lmy_sv0
	s_cmp_eq_u32 s98, 1
	s_cbranch_scc1 .Lmy_sv1
	s_branch .Lmy_sv_done
; __device__ __forceinline__ void gu_strip(Frame& F, int uidx, int par) {
;     ...
;     for (int kt = F.wave; kt < nkt; kt += 8) {
;         f32x4 v[16]; float gA, gB; d.k0 = 128 * kt; gu_load(v, gA, gB, d, lane);
; #pragma unroll
;         for (int jq = 0; jq < 4; ++jq) {
; #pragma unroll
;             for (int e2 = 0; e2 < 4; ++e2) {
;                 const float g = jq < 2 ? __shfl(gA, 32 * jq + 4 * kr + e2) : __shfl(gB, 32 * (jq - 2) + 4 * kr + e2);
; #pragma unroll
;                 for (int e = 0; e < 4; ++e) cm[e] = fmaxf(cm[e], fabsf(v[4 * jq + e2][e] * g));
;             }
;         }
;     }
; #pragma unroll
;     for (int e = 0; e < 4; ++e) { float m = cm[e]; m = fmaxf(m, __shfl_xor(m, 8)); m = fmaxf(m, __shfl_xor(m, 16)); m = fmaxf(m, __shfl_xor(m, 32)); cm[e] = m; }
;     if (kr == 0) { for (int e = 0; e < 4; ++e) part[F.wave * 32 + 4 * nq + e] = cm[e]; }
;     __syncthreads();
;     float inv[4];
; #pragma unroll
;     for (int e = 0; e < 4; ++e) {
;         float m = 0.f;
; #pragma unroll
;         for (int w = 0; w < 8; ++w) m = fmaxf(m, part[w * 32 + 4 * nq + e]);
;         inv[e] = m > 0.f ? 127.0f / m : 0.f;
;         if (F.wave == 0 && kr == 0) { const int n = d.n0 + 4 * nq + e; d.sb[d.il ? gu_dest(n, d.bj) : n] = m * (1.0f / 127.0f); }
;     }
;     for (int kt = F.wave; kt < nkt; kt += 8) {
;         f32x4 v[16]; float gA, gB; d.k0 = 128 * kt; gu_load(v, gA, gB, d, lane);
;         gu_finish_t<true, 0>(v, gA, gB, d, T, lane, inv);
;     }
.Lmy_sv0:
	v_mov_b32_e32 v122, v247
	v_mov_b32_e32 v123, v248
	v_mov_b32_e32 v124, v249
	v_mov_b32_e32 v125, v250
	v_mov_b32_e32 v126, v251
	v_mov_b32_e32 v127, v27
	v_mov_b32_e32 v128, v28
	v_mov_b32_e32 v129, v29
	v_mov_b32_e32 v130, v30
	v_mov_b32_e32 v131, v31
	v_mov_b32_e32 v132, v32
	v_mov_b32_e32 v133, v33
	v_mov_b32_e32 v134, v60
	v_mov_b32_e32 v135, v61
	v_mov_b32_e32 v136, v62
	v_mov_b32_e32 v137, v63
	v_mov_b32_e32 v138, v64
	v_mov_b32_e32 v139, v65
	v_mov_b32_e32 v140, v66
	v_mov_b32_e32 v141, v67
	v_mov_b32_e32 v142, v68
	v_mov_b32_e32 v143, v69
	v_mov_b32_e32 v144, v70
	v_mov_b32_e32 v145, v71
	v_mov_b32_e32 v146, v72
	v_mov_b32_e32 v147, v73
	v_mov_b32_e32 v148, v74
	v_mov_b32_e32 v149, v75
	v_mov_b32_e32 v150, v76
	v_mov_b32_e32 v151, v77
	v_mov_b32_e32 v152, v78
	v_mov_b32_e32 v153, v79
	v_mov_b32_e32 v154, v80
	v_mov_b32_e32 v155, v81
	v_mov_b32_e32 v156, v82
	v_mov_b32_e32 v157, v83
	v_mov_b32_e32 v158, v84
	v_mov_b32_e32 v159, v85
	v_mov_b32_e32 v160, v86
	v_mov_b32_e32 v161, v87
	v_mov_b32_e32 v162, v88
	v_mov_b32_e32 v163, v89
	v_mov_b32_e32 v164, v90
	v_mov_b32_e32 v165, v91
	v_mov_b32_e32 v166, v92
	v_mov_b32_e32 v167, v93
	v_mov_b32_e32 v168, v94
	v_mov_b32_e32 v169, v95
	v_mov_b32_e32 v170, v96
	v_mov_b32_e32 v171, v97
	v_mov_b32_e32 v172, v98
	v_mov_b32_e32 v173, v99
	v_mov_b32_e32 v174, v100
	v_mov_b32_e32 v175, v101
	v_mov_b32_e32 v176, v102
	v_mov_b32_e32 v177, v103
	v_mov_b32_e32 v178, v104
	v_mov_b32_e32 v179, v105
	v_mov_b32_e32 v180, v106
	v_mov_b32_e32 v181, v107
	v_mov_b32_e32 v182, v108
	v_mov_b32_e32 v183, v109
	v_mov_b32_e32 v184, v110
	v_mov_b32_e32 v185, v111
	s_branch .Lmy_sv_done
.Lmy_sv1:
	v_mov_b32_e32 v186, v247
	v_mov_b32_e32 v187, v248
	v_mov_b32_e32 v188, v249
	v_mov_b32_e32 v189, v250
	v_mov_b32_e32 v190, v251
	v_mov_b32_e32 v191, v27
	v_mov_b32_e32 v192, v28
	v_mov_b32_e32 v193, v29
	v_mov_b32_e32 v194, v30
	v_mov_b32_e32 v195, v31
	v_mov_b32_e32 v196, v32
	v_mov_b32_e32 v197, v33
	v_mov_b32_e32 v198, v60
	v_mov_b32_e32 v199, v61
	v_mov_b32_e32 v200, v62
	v_mov_b32_e32 v201, v63
	v_mov_b32_e32 v202, v64
	v_mov_b32_e32 v203, v65
	v_mov_b32_e32 v204, v66
	v_mov_b32_e32 v205, v67
	v_mov_b32_e32 v206, v68
	v_mov_b32_e32 v207, v69
	v_mov_b32_e32 v208, v70
	v_mov_b32_e32 v209, v71
	v_mov_b32_e32 v210, v72
	v_mov_b32_e32 v211, v73
	v_mov_b32_e32 v212, v74
	v_mov_b32_e32 v213, v75
	v_mov_b32_e32 v214, v76
	v_mov_b32_e32 v215, v77
	v_mov_b32_e32 v216, v78
	v_mov_b32_e32 v217, v79
	v_mov_b32_e32 v218, v80
	v_mov_b32_e32 v219, v81
	v_mov_b32_e32 v220, v82
	v_mov_b32_e32 v221, v83
	v_mov_b32_e32 v222, v84
	v_mov_b32_e32 v223, v85
	v_mov_b32_e32 v224, v86
	v_mov_b32_e32 v225, v87
	v_mov_b32_e32 v226, v88
	v_mov_b32_e32 v227, v89
	v_mov_b32_e32 v228, v90
	v_mov_b32_e32 v229, v91
	v_mov_b32_e32 v230, v92
	v_mov_b32_e32 v231, v93
	v_mov_b32_e32 v232, v94
	v_mov_b32_e32 v233, v95
	v_mov_b32_e32 v234, v96
	v_mov_b32_e32 v235, v97
	v_mov_b32_e32 v236, v98
	v_mov_b32_e32 v237, v99
	v_mov_b32_e32 v238, v100
	v_mov_b32_e32 v239, v101
	v_mov_b32_e32 v240, v102
	v_mov_b32_e32 v241, v103
	v_mov_b32_e32 v242, v104
	v_mov_b32_e32 v243, v105
	v_mov_b32_e32 v244, v106
	v_mov_b32_e32 v245, v107
	v_mov_b32_e32 v252, v108
	v_mov_b32_e32 v253, v109
	v_mov_b32_e32 v254, v110
	v_mov_b32_e32 v255, v111

; __device__ __forceinline__ void gu_load(f32x4 (&v)[16], float& gA, float& gB, const GUDesc& d, int lane) {
;     const int kr = lane >> 3, nq = lane & 7;
;     const float* __restrict__ src = d.W + (size_t)(d.k0 + 4 * kr) * d.N + d.n0 + 4 * nq;
;     gA = d.gain ? d.gain[d.k0 + lane] : 1.0f; gB = d.gain ? d.gain[d.k0 + 64 + lane] : 1.0f;
; #pragma unroll
;     for (int i = 0; i < 16; ++i) v[i] = *(const f32x4*)(src + (size_t)(32 * (i >> 2) + (i & 3)) * d.N);
; }
; __device__ __forceinline__ void gu_strip(Frame& F, int uidx, int par) {
;     ...
;     for (int kt = F.wave; kt < nkt; kt += 8) {
;         f32x4 v[16]; float gA, gB; d.k0 = 128 * kt; gu_load(v, gA, gB, d, lane);
;         gu_finish_t<true, 0>(v, gA, gB, d, T, lane, inv);
;     }
.LBB0_1098:
	s_lshr_b32 s98, s6, 3
	s_waitcnt vmcnt(0)
	s_bitcmp1_b32 s98, 0
	s_cbranch_scc1 .Lmy_pb_odd
	v_mov_b32_e32 v70, v122
	v_mov_b32_e32 v71, v123
	v_mov_b32_e32 v72, v124
	v_mov_b32_e32 v73, v125
	v_mov_b32_e32 v74, v126
	v_mov_b32_e32 v75, v127
	v_mov_b32_e32 v76, v128
	v_mov_b32_e32 v77, v129
	v_mov_b32_e32 v78, v130
	v_mov_b32_e32 v79, v131
	v_mov_b32_e32 v80, v132
	v_mov_b32_e32 v81, v133
	v_mov_b32_e32 v82, v134
	v_mov_b32_e32 v83, v135
	v_mov_b32_e32 v84, v136
	v_mov_b32_e32 v85, v137
	v_mov_b32_e32 v86, v138
	v_mov_b32_e32 v87, v139
	v_mov_b32_e32 v88, v140
	v_mov_b32_e32 v89, v141
	v_mov_b32_e32 v90, v142
	v_mov_b32_e32 v91, v143
	v_mov_b32_e32 v92, v144
	v_mov_b32_e32 v93, v145
	v_mov_b32_e32 v94, v146
	v_mov_b32_e32 v95, v147
	v_mov_b32_e32 v96, v148
	v_mov_b32_e32 v97, v149
	v_mov_b32_e32 v98, v150
	v_mov_b32_e32 v99, v151
	v_mov_b32_e32 v100, v152
	v_mov_b32_e32 v101, v153
	v_mov_b32_e32 v102, v154
	v_mov_b32_e32 v103, v155
	v_mov_b32_e32 v104, v156
	v_mov_b32_e32 v105, v157
	v_mov_b32_e32 v106, v158
	v_mov_b32_e32 v107, v159
	v_mov_b32_e32 v108, v160
	v_mov_b32_e32 v109, v161
	v_mov_b32_e32 v110, v162
	v_mov_b32_e32 v111, v163
	v_mov_b32_e32 v112, v164
	v_mov_b32_e32 v113, v165
	v_mov_b32_e32 v114, v166
	v_mov_b32_e32 v115, v167
	v_mov_b32_e32 v116, v168
	v_mov_b32_e32 v117, v169
	v_mov_b32_e32 v2, v170
	v_mov_b32_e32 v3, v171
	v_mov_b32_e32 v4, v172
	v_mov_b32_e32 v5, v173
	v_mov_b32_e32 v6, v174
	v_mov_b32_e32 v7, v175
	v_mov_b32_e32 v8, v176
	v_mov_b32_e32 v9, v177
	v_mov_b32_e32 v10, v178
	v_mov_b32_e32 v11, v179
	v_mov_b32_e32 v12, v180
	v_mov_b32_e32 v13, v181
	v_mov_b32_e32 v14, v182
	v_mov_b32_e32 v15, v183
	v_mov_b32_e32 v16, v184
	v_mov_b32_e32 v17, v185
	s_cmp_lt_u32 s98, 2
	s_cbranch_scc0 .Lmy_pb_after
	v_add_u32_e32 v247, 0x800, v67
	v_mad_u64_u32 v[248:249], s[20:21], s16, v247, 0
	v_lshl_add_u64 v[248:249], v[248:249], 2, v[26:27]
	global_load_dwordx4 v[122:125], v[248:249], off
	v_lshl_add_u64 v[248:249], v[248:249], 0, s[0:1]
	global_load_dwordx4 v[126:129], v[248:249], off
	v_lshl_add_u64 v[248:249], v[248:249], 0, s[0:1]
	global_load_dwordx4 v[130:133], v[248:249], off
	v_lshl_add_u64 v[248:249], v[248:249], 0, s[0:1]
	global_load_dwordx4 v[134:137], v[248:249], off
	v_lshl_add_u64 v[248:249], v[248:249], 0, s[18:19]
	global_load_dwordx4 v[138:141], v[248:249], off
	v_lshl_add_u64 v[248:249], v[248:249], 0, s[0:1]
	global_load_dwordx4 v[142:145], v[248:249], off
	v_lshl_add_u64 v[248:249], v[248:249], 0, s[0:1]
	global_load_dwordx4 v[146:149], v[248:249], off
	v_lshl_add_u64 v[248:249], v[248:249], 0, s[0:1]
	global_load_dwordx4 v[150:153], v[248:249], off
	v_lshl_add_u64 v[248:249], v[248:249], 0, s[18:19]
	global_load_dwordx4 v[154:157], v[248:249], off
	v_lshl_add_u64 v[248:249], v[248:249], 0, s[0:1]
	global_load_dwordx4 v[158:161], v[248:249], off
	v_lshl_add_u64 v[248:249], v[248:249], 0, s[0:1]
	global_load_dwordx4 v[162:165], v[248:249], off
	v_lshl_add_u64 v[248:249], v[248:249], 0, s[0:1]
	global_load_dwordx4 v[166:169], v[248:249], off
	v_lshl_add_u64 v[248:249], v[248:249], 0, s[18:19]
	global_load_dwordx4 v[170:173], v[248:249], off
	v_lshl_add_u64 v[248:249], v[248:249], 0, s[0:1]
	global_load_dwordx4 v[174:177], v[248:249], off
	v_lshl_add_u64 v[248:249], v[248:249], 0, s[0:1]
	global_load_dwordx4 v[178:181], v[248:249], off
	v_lshl_add_u64 v[248:249], v[248:249], 0, s[0:1]
	global_load_dwordx4 v[182:185], v[248:249], off
	s_branch .Lmy_pb_after
.Lmy_pb_odd:
	v_mov_b32_e32 v70, v186
	v_mov_b32_e32 v71, v187
	v_mov_b32_e32 v72, v188
	v_mov_b32_e32 v73, v189
	v_mov_b32_e32 v74, v190
	v_mov_b32_e32 v75, v191
	v_mov_b32_e32 v76, v192
	v_mov_b32_e32 v77, v193
	v_mov_b32_e32 v78, v194
	v_mov_b32_e32 v79, v195
	v_mov_b32_e32 v80, v196
	v_mov_b32_e32 v81, v197
	v_mov_b32_e32 v82, v198
	v_mov_b32_e32 v83, v199
	v_mov_b32_e32 v84, v200
	v_mov_b32_e32 v85, v201
	v_mov_b32_e32 v86, v202
	v_mov_b32_e32 v87, v203
	v_mov_b32_e32 v88, v204
	v_mov_b32_e32 v89, v205
	v_mov_b32_e32 v90, v206
	v_mov_b32_e32 v91, v207
	v_mov_b32_e32 v92, v208
	v_mov_b32_e32 v93, v209
	v_mov_b32_e32 v94, v210
	v_mov_b32_e32 v95, v211
	v_mov_b32_e32 v96, v212
	v_mov_b32_e32 v97, v213
	v_mov_b32_e32 v98, v214
	v_mov_b32_e32 v99, v215
	v_mov_b32_e32 v100, v216
	v_mov_b32_e32 v101, v217
	v_mov_b32_e32 v102, v218
	v_mov_b32_e32 v103, v219
	v_mov_b32_e32 v104, v220
	v_mov_b32_e32 v105, v221
	v_mov_b32_e32 v106, v222
	v_mov_b32_e32 v107, v223
	v_mov_b32_e32 v108, v224
	v_mov_b32_e32 v109, v225
	v_mov_b32_e32 v110, v226
	v_mov_b32_e32 v111, v227
	v_mov_b32_e32 v112, v228
	v_mov_b32_e32 v113, v229
	v_mov_b32_e32 v114, v230
	v_mov_b32_e32 v115, v231
	v_mov_b32_e32 v116, v232
	v_mov_b32_e32 v117, v233
	v_mov_b32_e32 v2, v234
	v_mov_b32_e32 v3, v235
	v_mov_b32_e32 v4, v236
	v_mov_b32_e32 v5, v237
	v_mov_b32_e32 v6, v238
	v_mov_b32_e32 v7, v239
	v_mov_b32_e32 v8, v240
	v_mov_b32_e32 v9, v241
	v_mov_b32_e32 v10, v242
	v_mov_b32_e32 v11, v243
	v_mov_b32_e32 v12, v244
	v_mov_b32_e32 v13, v245
	v_mov_b32_e32 v14, v252
	v_mov_b32_e32 v15, v253
	v_mov_b32_e32 v16, v254
	v_mov_b32_e32 v17, v255
	s_cmp_lt_u32 s98, 2
	s_cbranch_scc0 .Lmy_pb_after
	v_add_u32_e32 v247, 0x800, v67
	v_mad_u64_u32 v[248:249], s[20:21], s16, v247, 0
	v_lshl_add_u64 v[248:249], v[248:249], 2, v[26:27]
	global_load_dwordx4 v[186:189], v[248:249], off
	v_lshl_add_u64 v[248:249], v[248:249], 0, s[0:1]
	global_load_dwordx4 v[190:193], v[248:249], off
	v_lshl_add_u64 v[248:249], v[248:249], 0, s[0:1]
	global_load_dwordx4 v[194:197], v[248:249], off
	v_lshl_add_u64 v[248:249], v[248:249], 0, s[0:1]
	global_load_dwordx4 v[198:201], v[248:249], off
	v_lshl_add_u64 v[248:249], v[248:249], 0, s[18:19]
	global_load_dwordx4 v[202:205], v[248:249], off
	v_lshl_add_u64 v[248:249], v[248:249], 0, s[0:1]
	global_load_dwordx4 v[206:209], v[248:249], off
	v_lshl_add_u64 v[248:249], v[248:249], 0, s[0:1]
	global_load_dwordx4 v[210:213], v[248:249], off
	v_lshl_add_u64 v[248:249], v[248:249], 0, s[0:1]
	global_load_dwordx4 v[214:217], v[248:249], off
	v_lshl_add_u64 v[248:249], v[248:249], 0, s[18:19]
	global_load_dwordx4 v[218:221], v[248:249], off
	v_lshl_add_u64 v[248:249], v[248:249], 0, s[0:1]
	global_load_dwordx4 v[222:225], v[248:249], off
	v_lshl_add_u64 v[248:249], v[248:249], 0, s[0:1]
	global_load_dwordx4 v[226:229], v[248:249], off
	v_lshl_add_u64 v[248:249], v[248:249], 0, s[0:1]
	global_load_dwordx4 v[230:233], v[248:249], off
	v_lshl_add_u64 v[248:249], v[248:249], 0, s[18:19]
	global_load_dwordx4 v[234:237], v[248:249], off
	v_lshl_add_u64 v[248:249], v[248:249], 0, s[0:1]
	global_load_dwordx4 v[238:241], v[248:249], off
	v_lshl_add_u64 v[248:249], v[248:249], 0, s[0:1]
	global_load_dwordx4 v[242:245], v[248:249], off
	v_lshl_add_u64 v[248:249], v[248:249], 0, s[0:1]
	global_load_dwordx4 v[252:255], v[248:249], off
; __device__ __forceinline__ unsigned pack4_i8(float a, float b, float c, float d) {
;     unsigned w = __builtin_amdgcn_cvt_pk_u8_f32(a + 128.0f, 0u, 0u); w = __builtin_amdgcn_cvt_pk_u8_f32(b + 128.0f, 1u, w); w = __builtin_amdgcn_cvt_pk_u8_f32(c + 128.0f, 2u, w); w = __builtin_amdgcn_cvt_pk_u8_f32(d + 128.0f, 3u, w);
;     return w ^ 0x80808080u;
; }
; template <bool STRIP, int ROT>
; __device__ __forceinline__ void gu_finish_t(f32x4 (&v)[16], float gA, float gB, const GUDesc& d, LAS unsigned* T, int lane, const float (&sinv)[4]) {
;     ...
;     for (int jq = 0; jq < 4; ++jq) {
;         float g[4];
; #pragma unroll
;         for (int e2 = 0; e2 < 4; ++e2) g[e2] = jq < 2 ? __shfl(gA, 32 * jq + 4 * kr + e2) : __shfl(gB, 32 * (jq - 2) + 4 * kr + e2);
; #pragma unroll
;         for (int e = 0; e < 4; ++e)
;             T[(4 * nq + e) * 33 + 8 * jq + kr] = pack4_i8(v[4 * jq + 0][e] * g[0] * inv[e], v[4 * jq + 1][e] * g[1] * inv[e], v[4 * jq + 2][e] * g[2] * inv[e], v[4 * jq + 3][e] * g[3] * inv[e]);
;     }
.Lmy_pb_after:
	s_nop 0
	ds_bpermute_b32 v118, v41, v69
	ds_bpermute_b32 v119, v42, v69
	ds_bpermute_b32 v120, v43, v69
	ds_bpermute_b32 v121, v44, v69
	s_add_i32 s7, s6, 8
	v_add_u32_e32 v67, 0x400, v67
	v_add_u32_e32 v18, 0x400, v18
	s_cmp_lt_u32 s6, 24
	s_waitcnt lgkmcnt(3)
	v_mul_f32_e32 v70, v70, v118
	v_mul_f32_e32 v71, v71, v118
	s_waitcnt lgkmcnt(2)
	v_mul_f32_e32 v74, v74, v119
	v_fmaak_f32 v70, v63, v70, 0x43000000
	v_mul_f32_e32 v72, v72, v118
	v_mul_f32_e32 v75, v75, v119
	v_fmaak_f32 v71, v62, v71, 0x43000000
	s_waitcnt lgkmcnt(1)
	v_mul_f32_e32 v78, v78, v120
	v_cvt_pk_u8_f32 v70, v70, 0, 0
	v_fmaak_f32 v74, v63, v74, 0x43000000
	v_mul_f32_e32 v76, v76, v119
	v_fmaak_f32 v72, v61, v72, 0x43000000
	v_mul_f32_e32 v79, v79, v120
	v_cvt_pk_u8_f32 v71, v71, 0, 0
	v_fmaak_f32 v75, v62, v75, 0x43000000
	s_waitcnt lgkmcnt(0)
	v_mul_f32_e32 v82, v82, v121
	v_cvt_pk_u8_f32 v70, v74, 1, v70
	v_fmaak_f32 v74, v63, v78, 0x43000000
	v_mul_f32_e32 v80, v80, v120
	v_cvt_pk_u8_f32 v72, v72, 0, 0
	v_fmaak_f32 v76, v61, v76, 0x43000000
	v_mul_f32_e32 v78, v83, v121
	v_cvt_pk_u8_f32 v71, v75, 1, v71
	v_fmaak_f32 v75, v62, v79, 0x43000000
	v_cvt_pk_u8_f32 v70, v74, 2, v70
	v_fmaak_f32 v74, v63, v82, 0x43000000
	v_mul_f32_e32 v73, v73, v118
	v_mul_f32_e32 v79, v84, v121
	v_cvt_pk_u8_f32 v72, v76, 1, v72
	v_fmaak_f32 v76, v61, v80, 0x43000000
	v_cvt_pk_u8_f32 v71, v75, 2, v71
	v_fmaak_f32 v75, v62, v78, 0x43000000
	v_cvt_pk_u8_f32 v70, v74, 3, v70
	ds_bpermute_b32 v74, v45, v69
	v_mul_f32_e32 v77, v77, v119
	v_fmaak_f32 v73, v60, v73, 0x43000000
	v_cvt_pk_u8_f32 v72, v76, 2, v72
	v_fmaak_f32 v76, v61, v79, 0x43000000
	v_cvt_pk_u8_f32 v71, v75, 3, v71
	ds_bpermute_b32 v75, v46, v69
	v_mul_f32_e32 v81, v81, v120
	v_cvt_pk_u8_f32 v73, v73, 0, 0
	v_fmaak_f32 v77, v60, v77, 0x43000000
	v_cvt_pk_u8_f32 v72, v76, 3, v72
	ds_bpermute_b32 v76, v47, v69
	v_mul_f32_e32 v80, v85, v121
	v_cvt_pk_u8_f32 v73, v77, 1, v73
	v_fmaak_f32 v77, v60, v81, 0x43000000
	ds_bpermute_b32 v69, v48, v69
	v_cvt_pk_u8_f32 v73, v77, 2, v73
	v_fmaak_f32 v77, v60, v80, 0x43000000
	v_cvt_pk_u8_f32 v73, v77, 3, v73
	s_waitcnt lgkmcnt(3)
	v_mul_f32_e32 v77, v86, v74
	s_waitcnt lgkmcnt(2)
	v_mul_f32_e32 v78, v90, v75
	v_fmaak_f32 v77, v63, v77, 0x43000000
	s_waitcnt lgkmcnt(1)
	v_mul_f32_e32 v79, v94, v76
	v_cvt_pk_u8_f32 v77, v77, 0, 0
	v_fmaak_f32 v78, v63, v78, 0x43000000
	s_waitcnt lgkmcnt(0)
	v_mul_f32_e32 v80, v98, v69
	v_cvt_pk_u8_f32 v77, v78, 1, v77
	v_fmaak_f32 v78, v63, v79, 0x43000000
	v_cvt_pk_u8_f32 v77, v78, 2, v77
	v_fmaak_f32 v78, v63, v80, 0x43000000
	v_cvt_pk_u8_f32 v77, v78, 3, v77
	v_xor_b32_e32 v70, 0x80808080, v70
	v_xor_b32_e32 v77, 0x80808080, v77
	ds_write2_b32 v54, v70, v77 offset1:8
	v_mul_f32_e32 v70, v87, v74
	v_mul_f32_e32 v77, v91, v75
	v_fmaak_f32 v70, v62, v70, 0x43000000
	v_mul_f32_e32 v78, v95, v76
	v_cvt_pk_u8_f32 v70, v70, 0, 0
	v_fmaak_f32 v77, v62, v77, 0x43000000
	v_mul_f32_e32 v79, v99, v69
	v_cvt_pk_u8_f32 v70, v77, 1, v70
	v_fmaak_f32 v77, v62, v78, 0x43000000
	v_cvt_pk_u8_f32 v70, v77, 2, v70
	v_fmaak_f32 v77, v62, v79, 0x43000000
	v_cvt_pk_u8_f32 v70, v77, 3, v70
	v_xor_b32_e32 v71, 0x80808080, v71
	v_xor_b32_e32 v70, 0x80808080, v70
	ds_write2_b32 v54, v71, v70 offset0:33 offset1:41
	v_mul_f32_e32 v70, v88, v74
	v_mul_f32_e32 v71, v92, v75
	v_fmaak_f32 v70, v61, v70, 0x43000000
	v_mul_f32_e32 v77, v96, v76
	v_cvt_pk_u8_f32 v70, v70, 0, 0
	v_fmaak_f32 v71, v61, v71, 0x43000000
	v_mul_f32_e32 v78, v100, v69
	v_cvt_pk_u8_f32 v70, v71, 1, v70
	v_fmaak_f32 v71, v61, v77, 0x43000000
	v_cvt_pk_u8_f32 v70, v71, 2, v70
	v_fmaak_f32 v71, v61, v78, 0x43000000
	v_cvt_pk_u8_f32 v70, v71, 3, v70
	v_xor_b32_e32 v72, 0x80808080, v72
	v_xor_b32_e32 v70, 0x80808080, v70
	ds_write2_b32 v54, v72, v70 offset0:66 offset1:74
	v_mul_f32_e32 v70, v89, v74
	v_mul_f32_e32 v71, v93, v75
	v_fmaak_f32 v70, v60, v70, 0x43000000
	v_mul_f32_e32 v72, v97, v76
	v_cvt_pk_u8_f32 v70, v70, 0, 0
	v_fmaak_f32 v71, v60, v71, 0x43000000
	v_mul_f32_e32 v69, v101, v69
	v_cvt_pk_u8_f32 v70, v71, 1, v70
	v_fmaak_f32 v71, v60, v72, 0x43000000
	v_cvt_pk_u8_f32 v70, v71, 2, v70
	v_fmaak_f32 v69, v60, v69, 0x43000000
	v_cvt_pk_u8_f32 v69, v69, 3, v70
	ds_bpermute_b32 v70, v41, v68
	ds_bpermute_b32 v71, v42, v68
	ds_bpermute_b32 v72, v43, v68
	ds_bpermute_b32 v74, v44, v68
	v_xor_b32_e32 v73, 0x80808080, v73
	v_xor_b32_e32 v69, 0x80808080, v69
	ds_write2_b32 v54, v73, v69 offset0:99 offset1:107
	s_waitcnt lgkmcnt(4)
	v_mul_f32_e32 v69, v102, v70
	s_waitcnt lgkmcnt(3)
	v_mul_f32_e32 v73, v106, v71
	v_fmaak_f32 v69, v63, v69, 0x43000000
	s_waitcnt lgkmcnt(2)
	v_mul_f32_e32 v75, v110, v72
	v_cvt_pk_u8_f32 v69, v69, 0, 0
	v_fmaak_f32 v73, v63, v73, 0x43000000
	s_waitcnt lgkmcnt(1)
; #define LAS __attribute__((address_space(3)))
; __host__ __device__ __forceinline__ size_t blk8_off(int r, int k, int KT8_) { return ((size_t)((r >> 8) * KT8_ + (k >> 7)) * 256 + (size_t)(r & 255)) * 128 + (size_t)(k & 127); }
; #define LDS_WAIT() asm volatile("s_waitcnt lgkmcnt(0)" ::: "memory")
; template <bool STRIP, int ROT>
; __device__ __forceinline__ void gu_finish_t(f32x4 (&v)[16], float gA, float gB, const GUDesc& d, LAS unsigned* T, int lane, const float (&sinv)[4]) {
;     ...
;     for (int jq = 0; jq < 4; ++jq) {
;         float g[4];
; #pragma unroll
;         for (int e2 = 0; e2 < 4; ++e2) g[e2] = jq < 2 ? __shfl(gA, 32 * jq + 4 * kr + e2) : __shfl(gB, 32 * (jq - 2) + 4 * kr + e2);
; #pragma unroll
;         for (int e = 0; e < 4; ++e)
;             T[(4 * nq + e) * 33 + 8 * jq + kr] = pack4_i8(v[4 * jq + 0][e] * g[0] * inv[e], v[4 * jq + 1][e] * g[1] * inv[e], v[4 * jq + 2][e] * g[2] * inv[e], v[4 * jq + 3][e] * g[3] * inv[e]);
;     }
;     LDS_WAIT(); asm volatile("" ::: "memory");
;     const int nl = lane >> 3, c = lane & 7;
; #pragma unroll
;     for (int g4 = 0; g4 < 4; ++g4) {
;         const int nloc = 8 * g4 + nl, dr = d.il ? gu_dest(d.n0 + nloc, d.bj) : d.n0 + nloc;
;         const LAS unsigned* t = T + nloc * 33 + 4 * c;
;         u32x4 o; o.x = t[0]; o.y = t[1]; o.z = t[2]; o.w = t[3];
;         *(u32x4*)(d.WQ + blk8_off(dr, d.k0 + 16 * c, d.kt8)) = o;
;         if (!STRIP) if (d.k0 == 0 && c == 0) d.sb[dr] = __uint_as_float(d.cmax[dr]) * (1.0f / 127.0f);
;     }
;     LDS_WAIT(); asm volatile("" ::: "memory");
	v_mul_f32_e32 v76, v114, v74
	v_cvt_pk_u8_f32 v69, v73, 1, v69
	v_fmaak_f32 v73, v63, v75, 0x43000000
	v_cvt_pk_u8_f32 v69, v73, 2, v69
	v_fmaak_f32 v73, v63, v76, 0x43000000
	v_cvt_pk_u8_f32 v69, v73, 3, v69
	v_mul_f32_e32 v73, v103, v70
	v_mul_f32_e32 v75, v107, v71
	v_fmaak_f32 v73, v62, v73, 0x43000000
	v_mul_f32_e32 v76, v111, v72
	v_cvt_pk_u8_f32 v73, v73, 0, 0
	v_fmaak_f32 v75, v62, v75, 0x43000000
	v_mul_f32_e32 v77, v115, v74
	v_cvt_pk_u8_f32 v73, v75, 1, v73
	v_fmaak_f32 v75, v62, v76, 0x43000000
	v_cvt_pk_u8_f32 v73, v75, 2, v73
	v_fmaak_f32 v75, v62, v77, 0x43000000
	v_cvt_pk_u8_f32 v73, v75, 3, v73
	v_mul_f32_e32 v75, v104, v70
	v_mul_f32_e32 v70, v105, v70
	v_mul_f32_e32 v76, v108, v71
	v_mul_f32_e32 v71, v109, v71
	v_fmaak_f32 v70, v60, v70, 0x43000000
	v_mul_f32_e32 v77, v112, v72
	v_mul_f32_e32 v72, v113, v72
	v_cvt_pk_u8_f32 v70, v70, 0, 0
	v_fmaak_f32 v71, v60, v71, 0x43000000
	v_mul_f32_e32 v78, v116, v74
	v_mul_f32_e32 v74, v117, v74
	v_cvt_pk_u8_f32 v70, v71, 1, v70
	v_fmaak_f32 v71, v60, v72, 0x43000000
	v_cvt_pk_u8_f32 v70, v71, 2, v70
	v_fmaak_f32 v71, v60, v74, 0x43000000
	v_cvt_pk_u8_f32 v70, v71, 3, v70
	ds_bpermute_b32 v71, v45, v68
	ds_bpermute_b32 v72, v46, v68
	ds_bpermute_b32 v74, v47, v68
	ds_bpermute_b32 v68, v48, v68
	v_xor_b32_e32 v69, 0x80808080, v69
	s_waitcnt lgkmcnt(3)
	v_mul_f32_e32 v2, v2, v71
	s_waitcnt lgkmcnt(2)
	v_mul_f32_e32 v6, v6, v72
	v_fmaak_f32 v2, v63, v2, 0x43000000
	s_waitcnt lgkmcnt(1)
	v_mul_f32_e32 v10, v10, v74
	v_cvt_pk_u8_f32 v2, v2, 0, 0
	v_fmaak_f32 v6, v63, v6, 0x43000000
	s_waitcnt lgkmcnt(0)
	v_mul_f32_e32 v14, v14, v68
	v_cvt_pk_u8_f32 v2, v6, 1, v2
	v_fmaak_f32 v6, v63, v10, 0x43000000
	v_cvt_pk_u8_f32 v2, v6, 2, v2
	v_fmaak_f32 v6, v63, v14, 0x43000000
	v_cvt_pk_u8_f32 v2, v6, 3, v2
	v_xor_b32_e32 v2, 0x80808080, v2
	ds_write2_b32 v54, v69, v2 offset0:16 offset1:24
	v_mul_f32_e32 v2, v3, v71
	v_mul_f32_e32 v3, v7, v72
	v_fmaak_f32 v2, v62, v2, 0x43000000
	v_mul_f32_e32 v6, v11, v74
	v_cvt_pk_u8_f32 v2, v2, 0, 0
	v_fmaak_f32 v3, v62, v3, 0x43000000
	v_mul_f32_e32 v7, v15, v68
	v_cvt_pk_u8_f32 v2, v3, 1, v2
	v_fmaak_f32 v3, v62, v6, 0x43000000
	v_cvt_pk_u8_f32 v2, v3, 2, v2
	v_fmaak_f32 v3, v62, v7, 0x43000000
	v_cvt_pk_u8_f32 v2, v3, 3, v2
	v_xor_b32_e32 v73, 0x80808080, v73
	v_xor_b32_e32 v2, 0x80808080, v2
	ds_write2_b32 v54, v73, v2 offset0:49 offset1:57
	v_mul_f32_e32 v2, v4, v71
	v_fmaak_f32 v75, v61, v75, 0x43000000
	v_mul_f32_e32 v3, v8, v72
	v_fmaak_f32 v2, v61, v2, 0x43000000
	v_cvt_pk_u8_f32 v75, v75, 0, 0
	v_fmaak_f32 v76, v61, v76, 0x43000000
	v_mul_f32_e32 v4, v12, v74
	v_cvt_pk_u8_f32 v2, v2, 0, 0
	v_fmaak_f32 v3, v61, v3, 0x43000000
	v_cvt_pk_u8_f32 v75, v76, 1, v75
	v_fmaak_f32 v76, v61, v77, 0x43000000
	v_mul_f32_e32 v6, v16, v68
	v_cvt_pk_u8_f32 v2, v3, 1, v2
	v_fmaak_f32 v3, v61, v4, 0x43000000
	v_cvt_pk_u8_f32 v75, v76, 2, v75
	v_fmaak_f32 v76, v61, v78, 0x43000000
	v_cvt_pk_u8_f32 v2, v3, 2, v2
	v_fmaak_f32 v3, v61, v6, 0x43000000
	v_cvt_pk_u8_f32 v75, v76, 3, v75
	v_cvt_pk_u8_f32 v2, v3, 3, v2
	v_xor_b32_e32 v75, 0x80808080, v75
	v_xor_b32_e32 v2, 0x80808080, v2
	ds_write2_b32 v54, v75, v2 offset0:82 offset1:90
	v_mul_f32_e32 v2, v5, v71
	v_mul_f32_e32 v3, v9, v72
	v_fmaak_f32 v2, v60, v2, 0x43000000
	v_mul_f32_e32 v4, v13, v74
	v_cvt_pk_u8_f32 v2, v2, 0, 0
	v_fmaak_f32 v3, v60, v3, 0x43000000
	v_mul_f32_e32 v5, v17, v68
	v_cvt_pk_u8_f32 v2, v3, 1, v2
	v_fmaak_f32 v3, v60, v4, 0x43000000
	v_cvt_pk_u8_f32 v2, v3, 2, v2
	v_fmaak_f32 v3, v60, v5, 0x43000000
	v_cvt_pk_u8_f32 v2, v3, 3, v2
	v_xor_b32_e32 v70, 0x80808080, v70
	v_xor_b32_e32 v2, 0x80808080, v2
	ds_write2_b32 v54, v70, v2 offset0:115 offset1:123
	s_waitcnt lgkmcnt(0)
	ds_read2_b32 v[2:3], v55 offset1:1
	ds_read2_b32 v[4:5], v55 offset0:2 offset1:3
	v_add_u32_e32 v6, s6, v23
	v_ashrrev_i32_e32 v7, 31, v6
	v_lshlrev_b64 v[6:7], 15, v[6:7]
	v_lshl_add_u64 v[10:11], v[28:29], 0, v[6:7]
	v_add_u32_e32 v6, 0x420, v55
	v_add_u32_e32 v8, 0x428, v55
	ds_read2_b32 v[6:7], v6 offset1:1
	ds_read2_b32 v[8:9], v8 offset1:1
	s_waitcnt lgkmcnt(2)
	global_store_dwordx4 v[10:11], v[2:5], off
	s_nop 1
	v_add_u32_e32 v2, s6, v64
	v_ashrrev_i32_e32 v3, 31, v2
	v_lshlrev_b64 v[2:3], 15, v[2:3]
	v_lshl_add_u64 v[2:3], v[30:31], 0, v[2:3]
	s_waitcnt lgkmcnt(0)
	global_store_dwordx4 v[2:3], v[6:9], off
	v_add_u32_e32 v2, 0x840, v55
	v_add_u32_e32 v4, 0x848, v55
	ds_read2_b32 v[2:3], v2 offset1:1
	ds_read2_b32 v[4:5], v4 offset1:1
	v_add_u32_e32 v6, s6, v65
	v_ashrrev_i32_e32 v7, 31, v6
	v_lshlrev_b64 v[6:7], 15, v[6:7]
	v_lshl_add_u64 v[10:11], v[32:33], 0, v[6:7]
	v_add_u32_e32 v6, 0xc60, v55
	v_add_u32_e32 v8, 0xc68, v55
	ds_read2_b32 v[6:7], v6 offset1:1
	ds_read2_b32 v[8:9], v8 offset1:1
	s_waitcnt lgkmcnt(2)
	global_store_dwordx4 v[10:11], v[2:5], off
	s_nop 1
	v_add_u32_e32 v2, s6, v66
	v_ashrrev_i32_e32 v3, 31, v2
	v_lshlrev_b64 v[2:3], 15, v[2:3]
	v_lshl_add_u64 v[2:3], v[34:35], 0, v[2:3]
	s_waitcnt lgkmcnt(0)
	global_store_dwordx4 v[2:3], v[6:9], off
	s_waitcnt lgkmcnt(0)
	s_mov_b32 s6, s7
	s_cbranch_scc0 .LBB0_1073
